# ssd3 half staging: LDS-reuse barrier moved below the issue of the 9 staging loads (latency overlaps the barrier wait)
# speedup vs baseline: 1.0149x; 1.0149x over previous
.LBB0_39:
	v_readlane_b32 s6, v255, 8
	s_xor_b64 s[26:27], s[0:1], -1
	s_lshl_b32 s0, s4, 7
	v_readlane_b32 s7, v255, 9
	v_mov_b32_e32 v73, v179
	s_or_b32 s66, s6, s0
	v_readlane_b32 s6, v255, 18
	v_lshlrev_b32_e32 v66, 4, v73
	v_ashrrev_i32_e32 v74, 4, v73
	v_and_b32_e32 v66, 0xf0, v66
	v_mov_b32_e32 v67, v1
	v_readlane_b32 s7, v255, 19
	v_ashrrev_i32_e32 v75, 31, v74
	v_add_u32_e32 v72, 32, v66
	v_lshl_add_u64 v[70:71], s[6:7], 0, v[66:67]
	v_lshl_add_u64 v[66:67], s[66:67], 0, v[74:75]
	v_lshlrev_b64 v[66:67], 13, v[66:67]
	v_lshl_add_u64 v[66:67], v[70:71], 0, v[66:67]
	global_load_dwordx4 v[200:203], v[66:67], off
	s_movk_i32 s1, 0x110
	v_mad_u64_u32 v[74:75], s[6:7], v74, s1, v[72:73]
	v_mov_b32_e32 v226, v74
	s_cmp_lt_u32 s4, s35
	s_cselect_b64 s[54:55], -1, 0
	s_cmp_eq_u32 s4, s35
	s_cselect_b64 s[36:37], -1, 0
	s_cmp_gt_u32 s4, s35
	s_movk_i32 s28, 0x110
	s_cselect_b64 s[38:39], -1, 0
	v_or_b32_e32 v84, s0, v150
	v_add_u32_e32 v66, 0x200, v73
	v_ashrrev_i32_e32 v74, 4, v66
	v_ashrrev_i32_e32 v75, 31, v74
	v_lshl_add_u64 v[66:67], s[66:67], 0, v[74:75]
	v_lshlrev_b64 v[66:67], 13, v[66:67]
	v_lshl_add_u64 v[66:67], v[70:71], 0, v[66:67]
	global_load_dwordx4 v[204:207], v[66:67], off
	v_add_u32_e32 v66, 0x400, v73
	v_ashrrev_i32_e32 v74, 4, v66
	v_ashrrev_i32_e32 v75, 31, v74
	v_lshl_add_u64 v[66:67], s[66:67], 0, v[74:75]
	v_lshlrev_b64 v[66:67], 13, v[66:67]
	v_lshl_add_u64 v[66:67], v[70:71], 0, v[66:67]
	global_load_dwordx4 v[208:211], v[66:67], off
	v_add_u32_e32 v66, 0x600, v73
	v_ashrrev_i32_e32 v74, 4, v66
	v_ashrrev_i32_e32 v75, 31, v74
	v_lshl_add_u64 v[66:67], s[66:67], 0, v[74:75]
	v_lshlrev_b64 v[66:67], 13, v[66:67]
	v_lshl_add_u64 v[66:67], v[70:71], 0, v[66:67]
	global_load_dwordx4 v[212:215], v[66:67], off
	v_mov_b32_e32 v68, v179
	v_mov_b32_e32 v67, s67
	v_and_b32_e32 v70, 0x7f, v68
	v_or_b32_e32 v66, s66, v70
	v_ashrrev_i32_e32 v68, 1, v68
	v_lshlrev_b64 v[66:67], 13, v[66:67]
	v_and_b32_e32 v68, 0xffffffc0, v68
	v_lshl_add_u64 v[66:67], s[2:3], 0, v[66:67]
	v_ashrrev_i32_e32 v69, 31, v68
	v_lshl_add_u64 v[66:67], v[68:69], 1, v[66:67]
	v_mul_lo_u32 v72, v68, s1
	v_lshlrev_b32_e32 v73, 1, v70
	global_load_dwordx4 v[130:133], v[66:67], off
	v_readlane_b32 s1, v254, 4
	s_mov_b32 s66, 0
	s_nop 0
	v_add3_u32 v74, s1, v72, v73
	v_add3_u32 v72, s1, v73, v72
	global_load_dwordx4 v[134:137], v[66:67], off offset:16
	global_load_dwordx4 v[138:141], v[66:67], off offset:32
	global_load_dwordx4 v[192:195], v[66:67], off offset:48
	global_load_dwordx4 v[222:225], v[66:67], off offset:64
	s_barrier
	s_waitcnt vmcnt(8)
	ds_write_b128 v226, v[200:203] offset:34816
	global_load_dwordx4 v[200:203], v[66:67], off offset:80
	s_waitcnt vmcnt(8)
	ds_write_b128 v226, v[204:207] offset:43520
	global_load_dwordx4 v[204:207], v[66:67], off offset:96
	s_waitcnt vmcnt(8)
	ds_write_b128 v226, v[208:211] offset:52224
	global_load_dwordx4 v[208:211], v[66:67], off offset:112
	s_waitcnt vmcnt(8)
	ds_write_b128 v226, v[212:215] offset:60928
	s_waitcnt vmcnt(7)
	ds_write_b16 v74, v130
	ds_write_b16_d16_hi v72, v130 offset:272
	ds_write_b16 v72, v131 offset:544
	ds_write_b16_d16_hi v72, v131 offset:816
	ds_write_b16 v72, v132 offset:1088
	ds_write_b16_d16_hi v72, v132 offset:1360
	ds_write_b16 v74, v133 offset:1632
	ds_write_b16_d16_hi v72, v133 offset:1904
	s_waitcnt vmcnt(6)
	ds_write_b16 v72, v134 offset:2176
	ds_write_b16_d16_hi v72, v134 offset:2448
	ds_write_b16 v74, v135 offset:2720
	ds_write_b16_d16_hi v72, v135 offset:2992
	ds_write_b16 v72, v136 offset:3264
	ds_write_b16_d16_hi v72, v136 offset:3536
	ds_write_b16 v74, v137 offset:3808
	ds_write_b16_d16_hi v72, v137 offset:4080
	s_waitcnt vmcnt(5)
	ds_write_b16 v72, v138 offset:4352
	ds_write_b16_d16_hi v72, v138 offset:4624
	ds_write_b16 v74, v139 offset:4896
	ds_write_b16_d16_hi v72, v139 offset:5168
	ds_write_b16 v72, v140 offset:5440
	ds_write_b16_d16_hi v72, v140 offset:5712
	ds_write_b16 v74, v141 offset:5984
	ds_write_b16_d16_hi v72, v141 offset:6256
	s_waitcnt vmcnt(4)
	ds_write_b16 v72, v192 offset:6528
	ds_write_b16_d16_hi v72, v192 offset:6800
	ds_write_b16 v74, v193 offset:7072
	ds_write_b16_d16_hi v72, v193 offset:7344
	ds_write_b16 v72, v194 offset:7616
	ds_write_b16_d16_hi v72, v194 offset:7888
	ds_write_b16 v74, v195 offset:8160
	ds_write_b16_d16_hi v72, v195 offset:8432
	s_waitcnt vmcnt(3)
	ds_write_b16 v72, v222 offset:8704
	ds_write_b16_d16_hi v72, v222 offset:8976
	ds_write_b16 v74, v223 offset:9248
	ds_write_b16_d16_hi v72, v223 offset:9520
	ds_write_b16 v72, v224 offset:9792
	ds_write_b16_d16_hi v72, v224 offset:10064
	ds_write_b16 v74, v225 offset:10336
	ds_write_b16_d16_hi v72, v225 offset:10608
	s_waitcnt vmcnt(2)
	ds_write_b16 v72, v200 offset:10880
	ds_write_b16_d16_hi v72, v200 offset:11152
	ds_write_b16 v74, v201 offset:11424
	ds_write_b16_d16_hi v72, v201 offset:11696
	ds_write_b16 v72, v202 offset:11968
	ds_write_b16_d16_hi v72, v202 offset:12240
	ds_write_b16 v74, v203 offset:12512
	ds_write_b16_d16_hi v72, v203 offset:12784
	s_waitcnt vmcnt(1)
	ds_write_b16 v72, v204 offset:13056
	ds_write_b16_d16_hi v72, v204 offset:13328
	ds_write_b16 v74, v205 offset:13600
	ds_write_b16_d16_hi v72, v205 offset:13872
	ds_write_b16 v72, v206 offset:14144
	ds_write_b16_d16_hi v72, v206 offset:14416
	ds_write_b16 v74, v207 offset:14688
	ds_write_b16_d16_hi v72, v207 offset:14960
	s_waitcnt vmcnt(0)
	ds_write_b16 v72, v208 offset:15232
	ds_write_b16_d16_hi v72, v208 offset:15504
	ds_write_b16 v74, v209 offset:15776
	ds_write_b16_d16_hi v72, v209 offset:16048
	ds_write_b16 v72, v210 offset:16320
	ds_write_b16_d16_hi v72, v210 offset:16592
	ds_write_b16 v74, v211 offset:16864
	ds_write_b16_d16_hi v72, v211 offset:17136
	s_waitcnt lgkmcnt(0)
	s_barrier
	s_branch .LBB0_42
